# P0 x->bf16 loop: two rows (8 loads) in flight per wave
# speedup vs baseline: 1.0004x; 1.0004x over previous
.LBB0_55:
	s_add_i32 s5, s4, s52
	s_cmpk_gt_i32 s5, 0x7fff
	s_cbranch_scc1 .Lxn_one
	global_load_dwordx4 v[6:9], v[2:3], off offset:-2048
	global_load_dwordx4 v[14:17], v[2:3], off offset:-1024
	global_load_dwordx4 v[18:21], v[2:3], off
	global_load_dwordx4 v[22:25], v[2:3], off offset:1024
	v_lshl_add_u64 v[2:3], v[2:3], 0, s[2:3]
	global_load_dwordx4 v[26:29], v[2:3], off offset:-2048
	global_load_dwordx4 v[30:33], v[2:3], off offset:-1024
	global_load_dwordx4 v[34:37], v[2:3], off
	global_load_dwordx4 v[38:41], v[2:3], off offset:1024
	v_lshl_add_u64 v[2:3], v[2:3], 0, s[2:3]
	s_add_i32 s4, s5, s52
	s_waitcnt vmcnt(7)
	v_cvt_pk_bf16_f32 v6, v6, v7
	v_cvt_pk_bf16_f32 v7, v8, v9
	global_store_dwordx2 v[4:5], v[6:7], off offset:-1536
	s_waitcnt vmcnt(7)
	v_cvt_pk_bf16_f32 v14, v14, v15
	v_cvt_pk_bf16_f32 v15, v16, v17
	global_store_dwordx2 v[4:5], v[14:15], off offset:-1024
	s_waitcnt vmcnt(7)
	v_cvt_pk_bf16_f32 v18, v18, v19
	v_cvt_pk_bf16_f32 v19, v20, v21
	global_store_dwordx2 v[4:5], v[18:19], off offset:-512
	s_waitcnt vmcnt(7)
	v_cvt_pk_bf16_f32 v22, v22, v23
	v_cvt_pk_bf16_f32 v23, v24, v25
	global_store_dwordx2 v[4:5], v[22:23], off
	v_lshl_add_u64 v[4:5], v[4:5], 0, s[0:1]
	s_waitcnt vmcnt(7)
	v_cvt_pk_bf16_f32 v26, v26, v27
	v_cvt_pk_bf16_f32 v27, v28, v29
	global_store_dwordx2 v[4:5], v[26:27], off offset:-1536
	s_waitcnt vmcnt(7)
	v_cvt_pk_bf16_f32 v30, v30, v31
	v_cvt_pk_bf16_f32 v31, v32, v33
	global_store_dwordx2 v[4:5], v[30:31], off offset:-1024
	s_waitcnt vmcnt(7)
	v_cvt_pk_bf16_f32 v34, v34, v35
	v_cvt_pk_bf16_f32 v35, v36, v37
	global_store_dwordx2 v[4:5], v[34:35], off offset:-512
	s_waitcnt vmcnt(7)
	v_cvt_pk_bf16_f32 v38, v38, v39
	v_cvt_pk_bf16_f32 v39, v40, v41
	global_store_dwordx2 v[4:5], v[38:39], off
	v_lshl_add_u64 v[4:5], v[4:5], 0, s[0:1]
	s_cmpk_gt_i32 s4, 0x7fff
	s_cbranch_scc0 .LBB0_55
	s_branch .LBB0_56
.Lxn_one:
	global_load_dwordx4 v[6:9], v[2:3], off offset:-2048
	global_load_dwordx4 v[14:17], v[2:3], off offset:-1024
	global_load_dwordx4 v[18:21], v[2:3], off
	global_load_dwordx4 v[22:25], v[2:3], off offset:1024
	s_waitcnt vmcnt(3)
	v_cvt_pk_bf16_f32 v6, v6, v7
	v_cvt_pk_bf16_f32 v7, v8, v9
	global_store_dwordx2 v[4:5], v[6:7], off offset:-1536
	s_waitcnt vmcnt(3)
	v_cvt_pk_bf16_f32 v14, v14, v15
	v_cvt_pk_bf16_f32 v15, v16, v17
	global_store_dwordx2 v[4:5], v[14:15], off offset:-1024
	s_waitcnt vmcnt(3)
	v_cvt_pk_bf16_f32 v18, v18, v19
	v_cvt_pk_bf16_f32 v19, v20, v21
	global_store_dwordx2 v[4:5], v[18:19], off offset:-512
	s_waitcnt vmcnt(3)
	v_cvt_pk_bf16_f32 v22, v22, v23
	v_cvt_pk_bf16_f32 v23, v24, v25
	global_store_dwordx2 v[4:5], v[22:23], off
